# final RMSNorm output stores write-through (sc1); on top of v28
# speedup vs baseline: 1.0072x; 1.0072x over previous
; __device__ __forceinline__ float bflo(unsigned w) { return __uint_as_float(w << 16); }
; __device__ __forceinline__ float bfhi(unsigned w) { return __uint_as_float(w & 0xffff0000u); }
; #define LANE_IDS() int tid_l = threadIdx.x; asm volatile("" : "+v"(tid_l)); const int tid = tid_l, lane = tid & 63, wave = __builtin_amdgcn_readfirstlane(tid >> 6), gw = blockIdx.x * 8 + wave, NGW = gridDim.x * 8; (void)gw; (void)NGW; (void)lane
; __global__ void __launch_bounds__(512, 2) fwd_mega(Args a) {
;     ...
;     {
;         LANE_IDS();
;         const float* ssf = SS + (size_t)12 * M * 16;
;         f32x4 gv[4];
; #pragma unroll
;         for (int j = 0; j < 4; ++j) gv[j] = *((const f32x4*)a.final_norm + lane + 64 * j);
;         for (int row = gw; row < M; row += NGW) {
;             const float rs = row_rstd(ssf, row);
;             f32x4* orow = (f32x4*)(a.out + (size_t)row * D) + lane; const u32x2* xr = (const u32x2*)(XB + (size_t)row * D) + lane;
; #pragma unroll
;             for (int j = 0; j < 4; ++j) { const u32x2 w = xr[64 * j]; orow[64 * j] = (f32x4){bflo(w.x), bfhi(w.x), bflo(w.y), bfhi(w.y)} * rs * gv[j]; }
;         }
.Lfn_loop:
	s_mov_b32 s20, s0
	s_lshl_b32 s12, s20, 6
	s_add_u32 s12, s64, s12
	s_addc_u32 s13, s65, 0
	s_add_u32 s12, s12, 0x18680000
	s_addc_u32 s13, s13, 0
	global_load_dwordx4 v[48:51], v17, s[12:13]
	global_load_dwordx4 v[52:55], v17, s[12:13] offset:16
	global_load_dwordx4 v[56:59], v17, s[12:13] offset:32
	global_load_dwordx4 v[60:63], v17, s[12:13] offset:48
	s_lshl_b32 s14, s20, 11
	s_add_u32 s14, s64, s14
	s_addc_u32 s15, s65, 0
	s_add_u32 s14, s14, 0x6280000
	s_addc_u32 s15, s15, 0
	global_load_dwordx2 v[64:65], v40, s[14:15]
	global_load_dwordx2 v[66:67], v40, s[14:15] offset:512
	global_load_dwordx2 v[68:69], v40, s[14:15] offset:1024
	global_load_dwordx2 v[70:71], v40, s[14:15] offset:1536
	s_mul_i32 s21, s16, 1
	s_add_i32 s21, s21, s0
	s_cmp_gt_i32 s21, 0x3fff
	s_cselect_b32 s21, s0, s21
	s_lshl_b32 s12, s21, 6
	s_add_u32 s12, s64, s12
	s_addc_u32 s13, s65, 0
	s_add_u32 s12, s12, 0x18680000
	s_addc_u32 s13, s13, 0
	global_load_dwordx4 v[72:75], v17, s[12:13]
	global_load_dwordx4 v[76:79], v17, s[12:13] offset:16
	global_load_dwordx4 v[80:83], v17, s[12:13] offset:32
	global_load_dwordx4 v[84:87], v17, s[12:13] offset:48
	s_lshl_b32 s14, s21, 11
	s_add_u32 s14, s64, s14
	s_addc_u32 s15, s65, 0
	s_add_u32 s14, s14, 0x6280000
	s_addc_u32 s15, s15, 0
	global_load_dwordx2 v[88:89], v40, s[14:15]
	global_load_dwordx2 v[90:91], v40, s[14:15] offset:512
	global_load_dwordx2 v[92:93], v40, s[14:15] offset:1024
	global_load_dwordx2 v[94:95], v40, s[14:15] offset:1536
	s_mul_i32 s22, s16, 2
	s_add_i32 s22, s22, s0
	s_cmp_gt_i32 s22, 0x3fff
	s_cselect_b32 s22, s0, s22
	s_lshl_b32 s12, s22, 6
	s_add_u32 s12, s64, s12
	s_addc_u32 s13, s65, 0
	s_add_u32 s12, s12, 0x18680000
	s_addc_u32 s13, s13, 0
	global_load_dwordx4 v[96:99], v17, s[12:13]
	global_load_dwordx4 v[100:103], v17, s[12:13] offset:16
	global_load_dwordx4 v[104:107], v17, s[12:13] offset:32
	global_load_dwordx4 v[108:111], v17, s[12:13] offset:48
	s_lshl_b32 s14, s22, 11
	s_add_u32 s14, s64, s14
	s_addc_u32 s15, s65, 0
	s_add_u32 s14, s14, 0x6280000
	s_addc_u32 s15, s15, 0
	global_load_dwordx2 v[112:113], v40, s[14:15]
	global_load_dwordx2 v[114:115], v40, s[14:15] offset:512
	global_load_dwordx2 v[116:117], v40, s[14:15] offset:1024
	global_load_dwordx2 v[118:119], v40, s[14:15] offset:1536
	s_mul_i32 s23, s16, 3
	s_add_i32 s23, s23, s0
	s_cmp_gt_i32 s23, 0x3fff
	s_cselect_b32 s23, s0, s23
	s_lshl_b32 s12, s23, 6
	s_add_u32 s12, s64, s12
	s_addc_u32 s13, s65, 0
	s_add_u32 s12, s12, 0x18680000
	s_addc_u32 s13, s13, 0
	global_load_dwordx4 v[120:123], v17, s[12:13]
	global_load_dwordx4 v[124:127], v17, s[12:13] offset:16
	global_load_dwordx4 v[128:131], v17, s[12:13] offset:32
	global_load_dwordx4 v[132:135], v17, s[12:13] offset:48
	s_lshl_b32 s14, s23, 11
	s_add_u32 s14, s64, s14
	s_addc_u32 s15, s65, 0
	s_add_u32 s14, s14, 0x6280000
	s_addc_u32 s15, s15, 0
	global_load_dwordx2 v[136:137], v40, s[14:15]
	global_load_dwordx2 v[138:139], v40, s[14:15] offset:512
	global_load_dwordx2 v[140:141], v40, s[14:15] offset:1024
	global_load_dwordx2 v[142:143], v40, s[14:15] offset:1536
	s_mov_b32 s1, 0x800000
	s_waitcnt vmcnt(24)
	v_pk_add_f32 v[48:49], v[48:49], v[52:53]
	v_pk_add_f32 v[50:51], v[50:51], v[54:55]
	v_pk_add_f32 v[56:57], v[56:57], v[60:61]
	v_pk_add_f32 v[58:59], v[58:59], v[62:63]
	v_pk_add_f32 v[48:49], v[48:49], v[56:57]
	v_pk_add_f32 v[50:51], v[50:51], v[58:59]
	v_add_f32_e32 v48, v48, v49
	v_add_f32_e32 v50, v50, v51
	v_add_f32_e32 v48, v48, v50
	v_fmamk_f32 v48, v48, 0x3a800000, v22
	v_mul_f32_e32 v49, 0x4b800000, v48
	v_cmp_gt_f32_e32 vcc, s1, v48
	s_nop 1
	v_cndmask_b32_e32 v48, v48, v49, vcc
	v_rsq_f32_e32 v48, v48
	s_nop 0
	v_mul_f32_e32 v49, 0x45800000, v48
	v_cndmask_b32_e32 v52, v48, v49, vcc
	s_lshl_b32 s14, s20, 12
	s_add_u32 s14, s50, s14
	s_addc_u32 s15, s51, 0
	v_lshlrev_b32_e32 v48, 16, v64
	v_and_b32_e32 v49, 0xffff0000, v64
	v_lshlrev_b32_e32 v50, 16, v65
	v_and_b32_e32 v51, 0xffff0000, v65
	v_pk_mul_f32 v[48:49], v[52:53], v[48:49] op_sel_hi:[0,1]
	v_pk_mul_f32 v[50:51], v[52:53], v[50:51] op_sel_hi:[0,1]
	v_pk_mul_f32 v[56:57], v[0:1], v[48:49]
	v_pk_mul_f32 v[58:59], v[2:3], v[50:51]
	global_store_dwordx4 v41, v[56:59], s[14:15] sc1
	v_lshlrev_b32_e32 v48, 16, v66
	v_and_b32_e32 v49, 0xffff0000, v66
	v_lshlrev_b32_e32 v50, 16, v67
	v_and_b32_e32 v51, 0xffff0000, v67
	v_pk_mul_f32 v[48:49], v[52:53], v[48:49] op_sel_hi:[0,1]
	v_pk_mul_f32 v[50:51], v[52:53], v[50:51] op_sel_hi:[0,1]
	v_pk_mul_f32 v[60:61], v[4:5], v[48:49]
	v_pk_mul_f32 v[62:63], v[6:7], v[50:51]
	global_store_dwordx4 v41, v[60:63], s[14:15] offset:1024 sc1
	s_nop 0
	v_lshlrev_b32_e32 v48, 16, v68
	v_and_b32_e32 v49, 0xffff0000, v68
	v_lshlrev_b32_e32 v50, 16, v69
	v_and_b32_e32 v51, 0xffff0000, v69
	v_pk_mul_f32 v[48:49], v[52:53], v[48:49] op_sel_hi:[0,1]
	v_pk_mul_f32 v[50:51], v[52:53], v[50:51] op_sel_hi:[0,1]
	v_pk_mul_f32 v[56:57], v[8:9], v[48:49]
	v_pk_mul_f32 v[58:59], v[10:11], v[50:51]
	global_store_dwordx4 v41, v[56:59], s[14:15] offset:2048 sc1
	s_nop 0
	v_lshlrev_b32_e32 v48, 16, v70
	v_and_b32_e32 v49, 0xffff0000, v70
	v_lshlrev_b32_e32 v50, 16, v71
	v_and_b32_e32 v51, 0xffff0000, v71
	v_pk_mul_f32 v[48:49], v[52:53], v[48:49] op_sel_hi:[0,1]
	v_pk_mul_f32 v[50:51], v[52:53], v[50:51] op_sel_hi:[0,1]
	v_pk_mul_f32 v[60:61], v[12:13], v[48:49]
	v_pk_mul_f32 v[62:63], v[14:15], v[50:51]
	global_store_dwordx4 v41, v[60:63], s[14:15] offset:3072 sc1
	s_nop 0
	s_waitcnt vmcnt(20)
; __device__ __forceinline__ float bflo(unsigned w) { return __uint_as_float(w << 16); }
; __device__ __forceinline__ float bfhi(unsigned w) { return __uint_as_float(w & 0xffff0000u); }
; #define LANE_IDS() int tid_l = threadIdx.x; asm volatile("" : "+v"(tid_l)); const int tid = tid_l, lane = tid & 63, wave = __builtin_amdgcn_readfirstlane(tid >> 6), gw = blockIdx.x * 8 + wave, NGW = gridDim.x * 8; (void)gw; (void)NGW; (void)lane
; __global__ void __launch_bounds__(512, 2) fwd_mega(Args a) {
;     ...
;     {
;         LANE_IDS();
;         const float* ssf = SS + (size_t)12 * M * 16;
;         f32x4 gv[4];
; #pragma unroll
;         for (int j = 0; j < 4; ++j) gv[j] = *((const f32x4*)a.final_norm + lane + 64 * j);
;         for (int row = gw; row < M; row += NGW) {
;             const float rs = row_rstd(ssf, row);
;             f32x4* orow = (f32x4*)(a.out + (size_t)row * D) + lane; const u32x2* xr = (const u32x2*)(XB + (size_t)row * D) + lane;
; #pragma unroll
;             for (int j = 0; j < 4; ++j) { const u32x2 w = xr[64 * j]; orow[64 * j] = (f32x4){bflo(w.x), bfhi(w.x), bflo(w.y), bfhi(w.y)} * rs * gv[j]; }
;         }
	v_pk_add_f32 v[72:73], v[72:73], v[76:77]
	v_pk_add_f32 v[74:75], v[74:75], v[78:79]
	v_pk_add_f32 v[80:81], v[80:81], v[84:85]
	v_pk_add_f32 v[82:83], v[82:83], v[86:87]
	v_pk_add_f32 v[72:73], v[72:73], v[80:81]
	v_pk_add_f32 v[74:75], v[74:75], v[82:83]
	v_add_f32_e32 v72, v72, v73
	v_add_f32_e32 v74, v74, v75
	v_add_f32_e32 v72, v72, v74
	v_fmamk_f32 v72, v72, 0x3a800000, v22
	v_mul_f32_e32 v73, 0x4b800000, v72
	v_cmp_gt_f32_e32 vcc, s1, v72
	s_nop 1
	v_cndmask_b32_e32 v72, v72, v73, vcc
	v_rsq_f32_e32 v72, v72
	s_nop 0
	v_mul_f32_e32 v73, 0x45800000, v72
	v_cndmask_b32_e32 v76, v72, v73, vcc
	s_lshl_b32 s14, s21, 12
	s_add_u32 s14, s50, s14
	s_addc_u32 s15, s51, 0
	v_lshlrev_b32_e32 v72, 16, v88
	v_and_b32_e32 v73, 0xffff0000, v88
	v_lshlrev_b32_e32 v74, 16, v89
	v_and_b32_e32 v75, 0xffff0000, v89
	v_pk_mul_f32 v[72:73], v[76:77], v[72:73] op_sel_hi:[0,1]
	v_pk_mul_f32 v[74:75], v[76:77], v[74:75] op_sel_hi:[0,1]
	v_pk_mul_f32 v[80:81], v[0:1], v[72:73]
	v_pk_mul_f32 v[82:83], v[2:3], v[74:75]
	global_store_dwordx4 v41, v[80:83], s[14:15] sc1
	v_lshlrev_b32_e32 v72, 16, v90
	v_and_b32_e32 v73, 0xffff0000, v90
	v_lshlrev_b32_e32 v74, 16, v91
	v_and_b32_e32 v75, 0xffff0000, v91
	v_pk_mul_f32 v[72:73], v[76:77], v[72:73] op_sel_hi:[0,1]
	v_pk_mul_f32 v[74:75], v[76:77], v[74:75] op_sel_hi:[0,1]
	v_pk_mul_f32 v[84:85], v[4:5], v[72:73]
	v_pk_mul_f32 v[86:87], v[6:7], v[74:75]
	global_store_dwordx4 v41, v[84:87], s[14:15] offset:1024 sc1
	s_nop 0
	v_lshlrev_b32_e32 v72, 16, v92
	v_and_b32_e32 v73, 0xffff0000, v92
	v_lshlrev_b32_e32 v74, 16, v93
	v_and_b32_e32 v75, 0xffff0000, v93
	v_pk_mul_f32 v[72:73], v[76:77], v[72:73] op_sel_hi:[0,1]
	v_pk_mul_f32 v[74:75], v[76:77], v[74:75] op_sel_hi:[0,1]
	v_pk_mul_f32 v[80:81], v[8:9], v[72:73]
	v_pk_mul_f32 v[82:83], v[10:11], v[74:75]
	global_store_dwordx4 v41, v[80:83], s[14:15] offset:2048 sc1
	s_nop 0
	v_lshlrev_b32_e32 v72, 16, v94
	v_and_b32_e32 v73, 0xffff0000, v94
	v_lshlrev_b32_e32 v74, 16, v95
	v_and_b32_e32 v75, 0xffff0000, v95
	v_pk_mul_f32 v[72:73], v[76:77], v[72:73] op_sel_hi:[0,1]
	v_pk_mul_f32 v[74:75], v[76:77], v[74:75] op_sel_hi:[0,1]
	v_pk_mul_f32 v[84:85], v[12:13], v[72:73]
	v_pk_mul_f32 v[86:87], v[14:15], v[74:75]
	global_store_dwordx4 v41, v[84:87], s[14:15] offset:3072 sc1
	s_nop 0
	s_waitcnt vmcnt(16)
	v_pk_add_f32 v[96:97], v[96:97], v[100:101]
	v_pk_add_f32 v[98:99], v[98:99], v[102:103]
	v_pk_add_f32 v[104:105], v[104:105], v[108:109]
	v_pk_add_f32 v[106:107], v[106:107], v[110:111]
	v_pk_add_f32 v[96:97], v[96:97], v[104:105]
	v_pk_add_f32 v[98:99], v[98:99], v[106:107]
	v_add_f32_e32 v96, v96, v97
	v_add_f32_e32 v98, v98, v99
	v_add_f32_e32 v96, v96, v98
	v_fmamk_f32 v96, v96, 0x3a800000, v22
	v_mul_f32_e32 v97, 0x4b800000, v96
	v_cmp_gt_f32_e32 vcc, s1, v96
	s_nop 1
	v_cndmask_b32_e32 v96, v96, v97, vcc
	v_rsq_f32_e32 v96, v96
	s_nop 0
	v_mul_f32_e32 v97, 0x45800000, v96
	v_cndmask_b32_e32 v100, v96, v97, vcc
	s_lshl_b32 s14, s22, 12
	s_add_u32 s14, s50, s14
	s_addc_u32 s15, s51, 0
	v_lshlrev_b32_e32 v96, 16, v112
	v_and_b32_e32 v97, 0xffff0000, v112
	v_lshlrev_b32_e32 v98, 16, v113
	v_and_b32_e32 v99, 0xffff0000, v113
	v_pk_mul_f32 v[96:97], v[100:101], v[96:97] op_sel_hi:[0,1]
	v_pk_mul_f32 v[98:99], v[100:101], v[98:99] op_sel_hi:[0,1]
	v_pk_mul_f32 v[104:105], v[0:1], v[96:97]
	v_pk_mul_f32 v[106:107], v[2:3], v[98:99]
	global_store_dwordx4 v41, v[104:107], s[14:15] sc1
	v_lshlrev_b32_e32 v96, 16, v114
	v_and_b32_e32 v97, 0xffff0000, v114
	v_lshlrev_b32_e32 v98, 16, v115
	v_and_b32_e32 v99, 0xffff0000, v115
	v_pk_mul_f32 v[96:97], v[100:101], v[96:97] op_sel_hi:[0,1]
	v_pk_mul_f32 v[98:99], v[100:101], v[98:99] op_sel_hi:[0,1]
	v_pk_mul_f32 v[108:109], v[4:5], v[96:97]
	v_pk_mul_f32 v[110:111], v[6:7], v[98:99]
	global_store_dwordx4 v41, v[108:111], s[14:15] offset:1024 sc1
	s_nop 0
	v_lshlrev_b32_e32 v96, 16, v116
	v_and_b32_e32 v97, 0xffff0000, v116
	v_lshlrev_b32_e32 v98, 16, v117
	v_and_b32_e32 v99, 0xffff0000, v117
	v_pk_mul_f32 v[96:97], v[100:101], v[96:97] op_sel_hi:[0,1]
	v_pk_mul_f32 v[98:99], v[100:101], v[98:99] op_sel_hi:[0,1]
	v_pk_mul_f32 v[104:105], v[8:9], v[96:97]
	v_pk_mul_f32 v[106:107], v[10:11], v[98:99]
	global_store_dwordx4 v41, v[104:107], s[14:15] offset:2048 sc1
	s_nop 0
	v_lshlrev_b32_e32 v96, 16, v118
	v_and_b32_e32 v97, 0xffff0000, v118
	v_lshlrev_b32_e32 v98, 16, v119
	v_and_b32_e32 v99, 0xffff0000, v119
	v_pk_mul_f32 v[96:97], v[100:101], v[96:97] op_sel_hi:[0,1]
	v_pk_mul_f32 v[98:99], v[100:101], v[98:99] op_sel_hi:[0,1]
	v_pk_mul_f32 v[108:109], v[12:13], v[96:97]
	v_pk_mul_f32 v[110:111], v[14:15], v[98:99]
	global_store_dwordx4 v41, v[108:111], s[14:15] offset:3072 sc1
	s_nop 0
	s_waitcnt vmcnt(12)
; __device__ __forceinline__ float bflo(unsigned w) { return __uint_as_float(w << 16); }
; __device__ __forceinline__ float bfhi(unsigned w) { return __uint_as_float(w & 0xffff0000u); }
; #define LANE_IDS() int tid_l = threadIdx.x; asm volatile("" : "+v"(tid_l)); const int tid = tid_l, lane = tid & 63, wave = __builtin_amdgcn_readfirstlane(tid >> 6), gw = blockIdx.x * 8 + wave, NGW = gridDim.x * 8; (void)gw; (void)NGW; (void)lane
; __global__ void __launch_bounds__(512, 2) fwd_mega(Args a) {
;     ...
;     {
;         LANE_IDS();
;         const float* ssf = SS + (size_t)12 * M * 16;
;         f32x4 gv[4];
; #pragma unroll
;         for (int j = 0; j < 4; ++j) gv[j] = *((const f32x4*)a.final_norm + lane + 64 * j);
;         for (int row = gw; row < M; row += NGW) {
;             const float rs = row_rstd(ssf, row);
;             f32x4* orow = (f32x4*)(a.out + (size_t)row * D) + lane; const u32x2* xr = (const u32x2*)(XB + (size_t)row * D) + lane;
; #pragma unroll
;             for (int j = 0; j < 4; ++j) { const u32x2 w = xr[64 * j]; orow[64 * j] = (f32x4){bflo(w.x), bfhi(w.x), bflo(w.y), bfhi(w.y)} * rs * gv[j]; }
;         }
	v_pk_add_f32 v[120:121], v[120:121], v[124:125]
	v_pk_add_f32 v[122:123], v[122:123], v[126:127]
	v_pk_add_f32 v[128:129], v[128:129], v[132:133]
	v_pk_add_f32 v[130:131], v[130:131], v[134:135]
	v_pk_add_f32 v[120:121], v[120:121], v[128:129]
	v_pk_add_f32 v[122:123], v[122:123], v[130:131]
	v_add_f32_e32 v120, v120, v121
	v_add_f32_e32 v122, v122, v123
	v_add_f32_e32 v120, v120, v122
	v_fmamk_f32 v120, v120, 0x3a800000, v22
	v_mul_f32_e32 v121, 0x4b800000, v120
	v_cmp_gt_f32_e32 vcc, s1, v120
	s_nop 1
	v_cndmask_b32_e32 v120, v120, v121, vcc
	v_rsq_f32_e32 v120, v120
	s_nop 0
	v_mul_f32_e32 v121, 0x45800000, v120
	v_cndmask_b32_e32 v124, v120, v121, vcc
	s_lshl_b32 s14, s23, 12
	s_add_u32 s14, s50, s14
	s_addc_u32 s15, s51, 0
	v_lshlrev_b32_e32 v120, 16, v136
	v_and_b32_e32 v121, 0xffff0000, v136
	v_lshlrev_b32_e32 v122, 16, v137
	v_and_b32_e32 v123, 0xffff0000, v137
	v_pk_mul_f32 v[120:121], v[124:125], v[120:121] op_sel_hi:[0,1]
	v_pk_mul_f32 v[122:123], v[124:125], v[122:123] op_sel_hi:[0,1]
	v_pk_mul_f32 v[128:129], v[0:1], v[120:121]
	v_pk_mul_f32 v[130:131], v[2:3], v[122:123]
	global_store_dwordx4 v41, v[128:131], s[14:15] sc1
	v_lshlrev_b32_e32 v120, 16, v138
	v_and_b32_e32 v121, 0xffff0000, v138
	v_lshlrev_b32_e32 v122, 16, v139
	v_and_b32_e32 v123, 0xffff0000, v139
	v_pk_mul_f32 v[120:121], v[124:125], v[120:121] op_sel_hi:[0,1]
	v_pk_mul_f32 v[122:123], v[124:125], v[122:123] op_sel_hi:[0,1]
	v_pk_mul_f32 v[132:133], v[4:5], v[120:121]
	v_pk_mul_f32 v[134:135], v[6:7], v[122:123]
	global_store_dwordx4 v41, v[132:135], s[14:15] offset:1024 sc1
	s_nop 0
	v_lshlrev_b32_e32 v120, 16, v140
	v_and_b32_e32 v121, 0xffff0000, v140
	v_lshlrev_b32_e32 v122, 16, v141
	v_and_b32_e32 v123, 0xffff0000, v141
	v_pk_mul_f32 v[120:121], v[124:125], v[120:121] op_sel_hi:[0,1]
	v_pk_mul_f32 v[122:123], v[124:125], v[122:123] op_sel_hi:[0,1]
	v_pk_mul_f32 v[128:129], v[8:9], v[120:121]
	v_pk_mul_f32 v[130:131], v[10:11], v[122:123]
	global_store_dwordx4 v41, v[128:131], s[14:15] offset:2048 sc1
	s_nop 0
	v_lshlrev_b32_e32 v120, 16, v142
	v_and_b32_e32 v121, 0xffff0000, v142
	v_lshlrev_b32_e32 v122, 16, v143
	v_and_b32_e32 v123, 0xffff0000, v143
	v_pk_mul_f32 v[120:121], v[124:125], v[120:121] op_sel_hi:[0,1]
	v_pk_mul_f32 v[122:123], v[124:125], v[122:123] op_sel_hi:[0,1]
	v_pk_mul_f32 v[132:133], v[12:13], v[120:121]
	v_pk_mul_f32 v[134:135], v[14:15], v[122:123]
	global_store_dwordx4 v41, v[132:135], s[14:15] offset:3072 sc1
	s_nop 0
	s_mul_i32 s12, s16, 4
	s_add_i32 s0, s0, s12
	s_cmpk_gt_i32 s0, 0x3fff
	s_cbranch_scc0 .Lfn_loop
